# GEMM K-loop scalars: k-offset advanced after its last use in the head (tail holds only the exit compare), A stage pointer from the advanced offset, next-tile pointer switch as an out-of-line branch in
# baseline (speedup 1.0000x reference)
.LBB0_760:
	s_add_i32 s38, s46, 2
	s_add_u32 s30, s44, s4
	s_addc_u32 s31, s45, s5
	v_add_u32_e32 v252, 0x10000, v193
	ds_read_b128 v[132:135], v252
	ds_read_b128 v[136:139], v252 offset:1024
	ds_read_b128 v[140:143], v252 offset:2048
	ds_read_b128 v[144:147], v252 offset:3072
	v_lshl_add_u64 v[190:191], v[128:129], 0, s[4:5]
	s_add_i32 m0, s19, 0xc000
	ds_read_b128 v[148:151], v202
	ds_read_b128 v[152:155], v202 offset:1024
	ds_read_b128 v[156:159], v202 offset:2048
	ds_read_b128 v[160:163], v202 offset:3072
	ds_read_b128 v[164:167], v202 offset:4096
	ds_read_b128 v[204:207], v202 offset:5120
	ds_read_b128 v[208:211], v202 offset:6144
	ds_read_b128 v[212:215], v202 offset:7168
	global_load_lds_dwordx4 v[190:191], off
	s_add_i32 m0, s19, 0xe000
	v_lshl_add_u64 v[190:191], v[130:131], 0, s[4:5]
	global_load_lds_dwordx4 v[190:191], off
	s_add_u32 s4, s4, 0x100
	s_addc_u32 s5, s5, 0
	s_add_u32 s8, s26, s4
	s_addc_u32 s9, s27, s5
	s_cmp_eq_u32 s71, s46
	s_cbranch_scc1 .Lksel
.Lksel_back:
	s_waitcnt lgkmcnt(8)
	s_barrier
	s_waitcnt lgkmcnt(0)
	v_mfma_f32_16x16x32_bf16 v[124:127], v[132:135], v[148:151], v[124:127]
	v_mfma_f32_16x16x32_bf16 v[120:123], v[140:143], v[148:151], v[120:123]
	v_mfma_f32_16x16x32_bf16 v[108:111], v[132:135], v[156:159], v[108:111]
	v_mfma_f32_16x16x32_bf16 v[104:107], v[140:143], v[156:159], v[104:107]
	v_mfma_f32_16x16x32_bf16 v[92:95], v[132:135], v[164:167], v[92:95]
	v_mfma_f32_16x16x32_bf16 v[88:91], v[140:143], v[164:167], v[88:91]
	v_mfma_f32_16x16x32_bf16 v[76:79], v[132:135], v[208:211], v[76:79]
	v_mfma_f32_16x16x32_bf16 v[72:75], v[140:143], v[208:211], v[72:75]
	v_mfma_f32_16x16x32_bf16 v[124:127], v[136:139], v[152:155], v[124:127]
	v_mfma_f32_16x16x32_bf16 v[120:123], v[144:147], v[152:155], v[120:123]
	v_mfma_f32_16x16x32_bf16 v[108:111], v[136:139], v[160:163], v[108:111]
	v_mfma_f32_16x16x32_bf16 v[104:107], v[144:147], v[160:163], v[104:107]
	v_mfma_f32_16x16x32_bf16 v[92:95], v[136:139], v[204:207], v[92:95]
	v_mfma_f32_16x16x32_bf16 v[88:91], v[144:147], v[204:207], v[88:91]
	v_mfma_f32_16x16x32_bf16 v[76:79], v[136:139], v[212:215], v[76:79]
	v_mfma_f32_16x16x32_bf16 v[72:75], v[144:147], v[212:215], v[72:75]
	s_barrier
	s_add_i32 s47, s53, 0x10000
	ds_read_b128 v[216:219], v252 offset:16384
	ds_read_b128 v[220:223], v252 offset:17408
	ds_read_b128 v[232:235], v252 offset:18432
	ds_read_b128 v[240:243], v252 offset:19456
	s_mov_b32 m0, s47
	v_lshl_add_u64 v[190:191], s[30:31], 0, v[180:181]
	global_load_lds_dwordx4 v[190:191], off
	s_add_i32 m0, s47, 0x2000
	v_lshl_add_u64 v[224:225], s[30:31], 0, v[176:177]
	global_load_lds_dwordx4 v[224:225], off
	s_barrier
	s_waitcnt lgkmcnt(0)
	v_mfma_f32_16x16x32_bf16 v[116:119], v[216:219], v[148:151], v[116:119]
	v_mfma_f32_16x16x32_bf16 v[112:115], v[232:235], v[148:151], v[112:115]
	v_mfma_f32_16x16x32_bf16 v[100:103], v[216:219], v[156:159], v[100:103]
	v_mfma_f32_16x16x32_bf16 v[96:99], v[232:235], v[156:159], v[96:99]
	v_mfma_f32_16x16x32_bf16 v[84:87], v[216:219], v[164:167], v[84:87]
	v_mfma_f32_16x16x32_bf16 v[80:83], v[232:235], v[164:167], v[80:83]
	v_mfma_f32_16x16x32_bf16 v[68:71], v[216:219], v[208:211], v[68:71]
	v_mfma_f32_16x16x32_bf16 v[64:67], v[232:235], v[208:211], v[64:67]
	v_mfma_f32_16x16x32_bf16 v[116:119], v[220:223], v[152:155], v[116:119]
	v_mfma_f32_16x16x32_bf16 v[112:115], v[240:243], v[152:155], v[112:115]
	v_mfma_f32_16x16x32_bf16 v[100:103], v[220:223], v[160:163], v[100:103]
	v_mfma_f32_16x16x32_bf16 v[96:99], v[240:243], v[160:163], v[96:99]
	v_mfma_f32_16x16x32_bf16 v[84:87], v[220:223], v[204:207], v[84:87]
	v_mfma_f32_16x16x32_bf16 v[80:83], v[240:243], v[204:207], v[80:83]
	v_mfma_f32_16x16x32_bf16 v[68:71], v[220:223], v[212:215], v[68:71]
	v_mfma_f32_16x16x32_bf16 v[64:67], v[240:243], v[212:215], v[64:67]
	s_mov_b32 m0, s19
	v_lshl_add_u64 v[244:245], s[8:9], 0, v[178:179]
	s_barrier
	ds_read_b128 v[148:151], v202 offset:16384
	ds_read_b128 v[152:155], v202 offset:17408
	ds_read_b128 v[156:159], v202 offset:18432
	ds_read_b128 v[160:163], v202 offset:19456
	ds_read_b128 v[164:167], v202 offset:20480
	ds_read_b128 v[204:207], v202 offset:21504
	ds_read_b128 v[208:211], v202 offset:22528
	ds_read_b128 v[212:215], v202 offset:23552
	global_load_lds_dwordx4 v[244:245], off
	s_mov_b32 m0, s21
	v_lshl_add_u64 v[246:247], s[8:9], 0, v[174:175]
	global_load_lds_dwordx4 v[246:247], off
	s_barrier
	s_waitcnt lgkmcnt(0)
	v_mfma_f32_16x16x32_bf16 v[60:63], v[132:135], v[148:151], v[60:63]
	v_mfma_f32_16x16x32_bf16 v[56:59], v[140:143], v[148:151], v[56:59]
	v_mfma_f32_16x16x32_bf16 v[44:47], v[132:135], v[156:159], v[44:47]
	v_mfma_f32_16x16x32_bf16 v[40:43], v[140:143], v[156:159], v[40:43]
	v_mfma_f32_16x16x32_bf16 v[28:31], v[132:135], v[164:167], v[28:31]
	v_mfma_f32_16x16x32_bf16 v[24:27], v[140:143], v[164:167], v[24:27]
	v_mfma_f32_16x16x32_bf16 v[12:15], v[132:135], v[208:211], v[12:15]
	v_mfma_f32_16x16x32_bf16 v[8:11], v[140:143], v[208:211], v[8:11]
	v_mfma_f32_16x16x32_bf16 v[60:63], v[136:139], v[152:155], v[60:63]
	v_mfma_f32_16x16x32_bf16 v[56:59], v[144:147], v[152:155], v[56:59]
	v_mfma_f32_16x16x32_bf16 v[44:47], v[136:139], v[160:163], v[44:47]
	v_mfma_f32_16x16x32_bf16 v[40:43], v[144:147], v[160:163], v[40:43]
	v_mfma_f32_16x16x32_bf16 v[28:31], v[136:139], v[204:207], v[28:31]
	v_mfma_f32_16x16x32_bf16 v[24:27], v[144:147], v[204:207], v[24:27]
	v_mfma_f32_16x16x32_bf16 v[12:15], v[136:139], v[212:215], v[12:15]
	v_mfma_f32_16x16x32_bf16 v[8:11], v[144:147], v[212:215], v[8:11]
	s_barrier
	s_add_u32 s30, s30, s90
	s_addc_u32 s31, s31, s91
	s_add_i32 s46, s53, 0x14000
	s_mov_b32 m0, s46
	v_lshl_add_u64 v[248:249], s[30:31], 0, v[180:181]
	global_load_lds_dwordx4 v[248:249], off
	s_add_i32 m0, s46, 0x2000
	v_lshl_add_u64 v[250:251], s[30:31], 0, v[176:177]
	global_load_lds_dwordx4 v[250:251], off
	s_waitcnt vmcnt(6)
	s_barrier
	v_mfma_f32_16x16x32_bf16 v[52:55], v[216:219], v[148:151], v[52:55]
	v_mfma_f32_16x16x32_bf16 v[48:51], v[232:235], v[148:151], v[48:51]
	v_mfma_f32_16x16x32_bf16 v[36:39], v[216:219], v[156:159], v[36:39]
	v_mfma_f32_16x16x32_bf16 v[32:35], v[232:235], v[156:159], v[32:35]
	v_mfma_f32_16x16x32_bf16 v[20:23], v[216:219], v[164:167], v[20:23]
	v_mfma_f32_16x16x32_bf16 v[16:19], v[232:235], v[164:167], v[16:19]
	v_mfma_f32_16x16x32_bf16 v[4:7], v[216:219], v[208:211], v[4:7]
	v_mfma_f32_16x16x32_bf16 v[0:3], v[232:235], v[208:211], v[0:3]
	v_mfma_f32_16x16x32_bf16 v[52:55], v[220:223], v[152:155], v[52:55]
	v_mfma_f32_16x16x32_bf16 v[48:51], v[240:243], v[152:155], v[48:51]
	v_mfma_f32_16x16x32_bf16 v[36:39], v[220:223], v[160:163], v[36:39]
	v_mfma_f32_16x16x32_bf16 v[32:35], v[240:243], v[160:163], v[32:35]
	v_mfma_f32_16x16x32_bf16 v[20:23], v[220:223], v[204:207], v[20:23]
	v_mfma_f32_16x16x32_bf16 v[16:19], v[240:243], v[204:207], v[16:19]
	v_mfma_f32_16x16x32_bf16 v[4:7], v[220:223], v[212:215], v[4:7]
	v_mfma_f32_16x16x32_bf16 v[0:3], v[240:243], v[212:215], v[0:3]
	s_barrier
	ds_read_b128 v[132:135], v252 offset:32768
	ds_read_b128 v[136:139], v252 offset:33792
	ds_read_b128 v[140:143], v252 offset:34816
	ds_read_b128 v[144:147], v252 offset:35840
	s_add_u32 s8, s8, s22
	s_addc_u32 s9, s9, s23
	s_mov_b32 m0, s64
	v_lshl_add_u64 v[216:217], s[8:9], 0, v[178:179]
	ds_read_b128 v[148:151], v202 offset:32768
	ds_read_b128 v[152:155], v202 offset:33792
	ds_read_b128 v[156:159], v202 offset:34816
	ds_read_b128 v[160:163], v202 offset:35840
	ds_read_b128 v[164:167], v202 offset:36864
	ds_read_b128 v[204:207], v202 offset:37888
	ds_read_b128 v[208:211], v202 offset:38912
	ds_read_b128 v[212:215], v202 offset:39936
	global_load_lds_dwordx4 v[216:217], off
	s_mov_b32 m0, s65
	v_lshl_add_u64 v[216:217], s[8:9], 0, v[174:175]
	global_load_lds_dwordx4 v[216:217], off
	s_waitcnt lgkmcnt(8)
	s_barrier
	s_waitcnt lgkmcnt(0)
	v_mfma_f32_16x16x32_bf16 v[124:127], v[132:135], v[148:151], v[124:127]
	v_mfma_f32_16x16x32_bf16 v[120:123], v[140:143], v[148:151], v[120:123]
	v_mfma_f32_16x16x32_bf16 v[108:111], v[132:135], v[156:159], v[108:111]
	v_mfma_f32_16x16x32_bf16 v[104:107], v[140:143], v[156:159], v[104:107]
	v_mfma_f32_16x16x32_bf16 v[92:95], v[132:135], v[164:167], v[92:95]
	v_mfma_f32_16x16x32_bf16 v[88:91], v[140:143], v[164:167], v[88:91]
	v_mfma_f32_16x16x32_bf16 v[76:79], v[132:135], v[208:211], v[76:79]
	v_mfma_f32_16x16x32_bf16 v[72:75], v[140:143], v[208:211], v[72:75]
	v_mfma_f32_16x16x32_bf16 v[124:127], v[136:139], v[152:155], v[124:127]
	v_mfma_f32_16x16x32_bf16 v[120:123], v[144:147], v[152:155], v[120:123]
	v_mfma_f32_16x16x32_bf16 v[108:111], v[136:139], v[160:163], v[108:111]
	v_mfma_f32_16x16x32_bf16 v[104:107], v[144:147], v[160:163], v[104:107]
	v_mfma_f32_16x16x32_bf16 v[92:95], v[136:139], v[204:207], v[92:95]
	v_mfma_f32_16x16x32_bf16 v[88:91], v[144:147], v[204:207], v[88:91]
	v_mfma_f32_16x16x32_bf16 v[76:79], v[136:139], v[212:215], v[76:79]
	v_mfma_f32_16x16x32_bf16 v[72:75], v[144:147], v[212:215], v[72:75]
	s_barrier
	s_add_i32 s9, s77, s53
	s_add_i32 m0, s9, 0xffffff80
	ds_read_b128 v[216:219], v252 offset:49152
	ds_read_b128 v[220:223], v252 offset:50176
	ds_read_b128 v[232:235], v252 offset:51200
	ds_read_b128 v[240:243], v252 offset:52224
	global_load_lds_dwordx4 v[190:191], off offset:128
	s_add_i32 m0, s9, 0x1f80
	s_nop 0
	global_load_lds_dwordx4 v[224:225], off offset:128
	s_barrier
	s_waitcnt lgkmcnt(0)
	v_mfma_f32_16x16x32_bf16 v[116:119], v[216:219], v[148:151], v[116:119]
	v_mfma_f32_16x16x32_bf16 v[112:115], v[232:235], v[148:151], v[112:115]
	v_mfma_f32_16x16x32_bf16 v[100:103], v[216:219], v[156:159], v[100:103]
	v_mfma_f32_16x16x32_bf16 v[96:99], v[232:235], v[156:159], v[96:99]
	v_mfma_f32_16x16x32_bf16 v[84:87], v[216:219], v[164:167], v[84:87]
	v_mfma_f32_16x16x32_bf16 v[80:83], v[232:235], v[164:167], v[80:83]
	v_mfma_f32_16x16x32_bf16 v[68:71], v[216:219], v[208:211], v[68:71]
	v_mfma_f32_16x16x32_bf16 v[64:67], v[232:235], v[208:211], v[64:67]
	v_mfma_f32_16x16x32_bf16 v[116:119], v[220:223], v[152:155], v[116:119]
	v_mfma_f32_16x16x32_bf16 v[112:115], v[240:243], v[152:155], v[112:115]
	v_mfma_f32_16x16x32_bf16 v[100:103], v[220:223], v[160:163], v[100:103]
	v_mfma_f32_16x16x32_bf16 v[96:99], v[240:243], v[160:163], v[96:99]
	v_mfma_f32_16x16x32_bf16 v[84:87], v[220:223], v[204:207], v[84:87]
	v_mfma_f32_16x16x32_bf16 v[80:83], v[240:243], v[204:207], v[80:83]
	v_mfma_f32_16x16x32_bf16 v[68:71], v[220:223], v[212:215], v[68:71]
	v_mfma_f32_16x16x32_bf16 v[64:67], v[240:243], v[212:215], v[64:67]
	s_add_i32 m0, s66, 0xffffff80
	s_barrier
	ds_read_b128 v[148:151], v202 offset:49152
	ds_read_b128 v[152:155], v202 offset:50176
	ds_read_b128 v[156:159], v202 offset:51200
	ds_read_b128 v[160:163], v202 offset:52224
	ds_read_b128 v[164:167], v202 offset:53248
	ds_read_b128 v[204:207], v202 offset:54272
	ds_read_b128 v[208:211], v202 offset:55296
	ds_read_b128 v[212:215], v202 offset:56320
	global_load_lds_dwordx4 v[244:245], off offset:128
	s_add_i32 m0, s67, 0xffffff80
	s_nop 0
	global_load_lds_dwordx4 v[246:247], off offset:128
	s_barrier
	s_waitcnt lgkmcnt(0)
	v_mfma_f32_16x16x32_bf16 v[60:63], v[132:135], v[148:151], v[60:63]
	v_mfma_f32_16x16x32_bf16 v[56:59], v[140:143], v[148:151], v[56:59]
	v_mfma_f32_16x16x32_bf16 v[44:47], v[132:135], v[156:159], v[44:47]
	v_mfma_f32_16x16x32_bf16 v[40:43], v[140:143], v[156:159], v[40:43]
	v_mfma_f32_16x16x32_bf16 v[28:31], v[132:135], v[164:167], v[28:31]
	v_mfma_f32_16x16x32_bf16 v[24:27], v[140:143], v[164:167], v[24:27]
	v_mfma_f32_16x16x32_bf16 v[12:15], v[132:135], v[208:211], v[12:15]
	v_mfma_f32_16x16x32_bf16 v[8:11], v[140:143], v[208:211], v[8:11]
	v_mfma_f32_16x16x32_bf16 v[60:63], v[136:139], v[152:155], v[60:63]
	v_mfma_f32_16x16x32_bf16 v[56:59], v[144:147], v[152:155], v[56:59]
	v_mfma_f32_16x16x32_bf16 v[44:47], v[136:139], v[160:163], v[44:47]
	v_mfma_f32_16x16x32_bf16 v[40:43], v[144:147], v[160:163], v[40:43]
	v_mfma_f32_16x16x32_bf16 v[28:31], v[136:139], v[204:207], v[28:31]
	v_mfma_f32_16x16x32_bf16 v[24:27], v[144:147], v[204:207], v[24:27]
	v_mfma_f32_16x16x32_bf16 v[12:15], v[136:139], v[212:215], v[12:15]
	v_mfma_f32_16x16x32_bf16 v[8:11], v[144:147], v[212:215], v[8:11]
	s_barrier
	s_add_i32 s8, s53, 0x1c000
	s_add_i32 m0, s8, 0xffffff80
	s_nop 0
	global_load_lds_dwordx4 v[248:249], off offset:128
	s_add_i32 m0, s8, 0x1f80
	s_nop 0
	global_load_lds_dwordx4 v[250:251], off offset:128
	s_waitcnt vmcnt(6)
	s_barrier
	v_mfma_f32_16x16x32_bf16 v[52:55], v[216:219], v[148:151], v[52:55]
	v_mfma_f32_16x16x32_bf16 v[48:51], v[232:235], v[148:151], v[48:51]
	v_mfma_f32_16x16x32_bf16 v[36:39], v[216:219], v[156:159], v[36:39]
	v_mfma_f32_16x16x32_bf16 v[32:35], v[232:235], v[156:159], v[32:35]
	v_mfma_f32_16x16x32_bf16 v[20:23], v[216:219], v[164:167], v[20:23]
	v_mfma_f32_16x16x32_bf16 v[16:19], v[232:235], v[164:167], v[16:19]
	v_mfma_f32_16x16x32_bf16 v[4:7], v[216:219], v[208:211], v[4:7]
	v_mfma_f32_16x16x32_bf16 v[0:3], v[232:235], v[208:211], v[0:3]
	v_mfma_f32_16x16x32_bf16 v[52:55], v[220:223], v[152:155], v[52:55]
	v_mfma_f32_16x16x32_bf16 v[48:51], v[240:243], v[152:155], v[48:51]
	v_mfma_f32_16x16x32_bf16 v[36:39], v[220:223], v[160:163], v[36:39]
	v_mfma_f32_16x16x32_bf16 v[32:35], v[240:243], v[160:163], v[32:35]
	v_mfma_f32_16x16x32_bf16 v[20:23], v[220:223], v[204:207], v[20:23]
	v_mfma_f32_16x16x32_bf16 v[16:19], v[240:243], v[204:207], v[16:19]
	v_mfma_f32_16x16x32_bf16 v[4:7], v[220:223], v[212:215], v[4:7]
	v_mfma_f32_16x16x32_bf16 v[0:3], v[240:243], v[212:215], v[0:3]
	s_cmp_ge_i32 s38, s68
	s_barrier
	s_cbranch_scc1 .Lkx_exit
	s_mov_b32 s46, s38
	s_andn2_b64 vcc, exec, s[96:97]
	s_cbranch_vccnz .LBB0_760
	s_branch .LBB0_754
.Lksel:
	s_mov_b32 s9, s13
	s_mov_b32 s8, s12
	s_mov_b32 s31, s57
	s_mov_b32 s30, s56
	s_branch .Lksel_back
